# strategy 4 arm C: v22 + one static s_setprio 1 for the OLDER wave half (waves 0-3, set in their align-barrier block from the first tile end), reset to 0 at each GEMM phase end
# baseline (speedup 1.0000x reference)
; #define PG8_STAGE(bufoff, gbase, voff) do { _Pragma("unroll") for (int _i = 0; _i < 2; ++_i) \
;         __builtin_amdgcn_global_load_lds((const unsigned*)((const char*)(gbase) + (voff)[_i]), (LAS unsigned*)(lds + (bufoff) + ldsw + _i * 8192), 16, 0, 0); } while (0)
; #define PG8_LDA(dst, b, h) do { _Pragma("unroll") for (int m = 0; m < 4; ++m) _Pragma("unroll") for (int k = 0; k < 2; ++k) dst[m][k] = *(const LAS bf16x8*)(lds + PG8_SA(b, h) + aoff + m * 2048 + k * 1024); } while (0)
; #define PG8_LDB(dst, b, h) do { _Pragma("unroll") for (int n = 0; n < 2; ++n) _Pragma("unroll") for (int k = 0; k < 2; ++k) dst[n][k] = *(const LAS bf16x8*)(lds + PG8_SB(b, h) + boff + n * 2048 + k * 1024); } while (0)
; #define PG8_MMA(ai, bj, At, Bt) do { __builtin_amdgcn_s_setprio(1); _Pragma("unroll") for (int m = 0; m < 4; ++m) _Pragma("unroll") for (int n = 0; n < 2; ++n) _Pragma("unroll") for (int k = 0; k < 2; ++k) \
;         acc[ai][bj][m][n] = __builtin_amdgcn_mfma_f32_16x16x32_bf16(Bt[n][k], At[m][k], acc[ai][bj][m][n], 0, 0, 0); __builtin_amdgcn_s_setprio(0); } while (0)
; template <class Epi, class Sched>
; __device__ __forceinline__ void gemm_phase(LAS unsigned char* lds, const int lda, const int ldb, const int K, const Sched& S, const Epi& E) {
;     ...
;             PG8_LDB(B0, 0, 0); PG8_LDB(B1, 0, 1); PG8_SCHED; PG8_LDA(At, 0, 0); PG8_STAGE(PG8_SA(1, 1), a1 + hstepA, voffA);
;             PG8_WAIT_V(8); PG8_WAIT_L(0); PG8_BAR; PG8_MMA(0, 0, At, B0); PG8_MMA(0, 1, At, B1); PG8_BAR; PG8_SCHED;
;             PG8_LDA(At, 0, 1); PG8_STAGE(PG8_SB(0, 0), b2, voffB); PG8_STAGE(PG8_SB(0, 1), b2 + hstepB, voffB); PG8_STAGE(PG8_SA(0, 0), a2, voffA);
;             PG8_WAIT_V(8); PG8_WAIT_L(0); PG8_BAR; PG8_MMA(1, 0, At, B0); PG8_MMA(1, 1, At, B1); PG8_BAR; PG8_SCHED;
;             PG8_LDB(B0, 1, 0); PG8_LDB(B1, 1, 1); PG8_SCHED; PG8_LDA(At, 1, 0); PG8_STAGE(PG8_SA(0, 1), a2 + hstepA, voffA);
;             PG8_WAIT_V(8); PG8_WAIT_L(0); PG8_BAR; PG8_MMA(0, 0, At, B0); PG8_MMA(0, 1, At, B1); PG8_BAR; PG8_SCHED;
;             PG8_LDA(At, 1, 1); PG8_STAGE(PG8_SB(1, 0), b3, voffB); PG8_STAGE(PG8_SB(1, 1), b3 + hstepB, voffB); PG8_STAGE(PG8_SA(1, 0), a3, voffA);
;             PG8_WAIT_V(8); PG8_WAIT_L(0); PG8_BAR;
;             if (last) E.pre(cur, wr, fr, rsv);
;             PG8_MMA(1, 0, At, B0); PG8_MMA(1, 1, At, B1); PG8_BAR; PG8_SCHED;
;         }
;         if (wr == 0) PG8_BAR;
.LBB0_244:
	ds_read_b128 v[130:133], v217
	ds_read_b128 v[134:137], v217 offset:1024
	ds_read_b128 v[138:141], v217 offset:2048
	ds_read_b128 v[142:145], v217 offset:3072
	ds_read_b128 v[146:149], v218
	ds_read_b128 v[150:153], v218 offset:1024
	ds_read_b128 v[154:157], v218 offset:2048
	ds_read_b128 v[158:161], v218 offset:3072
	ds_read_b128 v[162:165], v219
	ds_read_b128 v[166:169], v219 offset:1024
	ds_read_b128 v[170:173], v219 offset:2048
	ds_read_b128 v[174:177], v219 offset:3072
	ds_read_b128 v[178:181], v219 offset:4096
	ds_read_b128 v[182:185], v219 offset:5120
	ds_read_b128 v[186:189], v219 offset:6144
	ds_read_b128 v[190:193], v219 offset:7168
	s_and_b64 vcc, exec, s[10:11]
	s_cbranch_vccz .LBB0_246
	s_setprio 1
	s_barrier

; #define PG8_STAGE(bufoff, gbase, voff) do { _Pragma("unroll") for (int _i = 0; _i < 2; ++_i) \
;         __builtin_amdgcn_global_load_lds((const unsigned*)((const char*)(gbase) + (voff)[_i]), (LAS unsigned*)(lds + (bufoff) + ldsw + _i * 8192), 16, 0, 0); } while (0)
; #define PG8_LDA(dst, b, h) do { _Pragma("unroll") for (int m = 0; m < 4; ++m) _Pragma("unroll") for (int k = 0; k < 2; ++k) dst[m][k] = *(const LAS bf16x8*)(lds + PG8_SA(b, h) + aoff + m * 2048 + k * 1024); } while (0)
; #define PG8_LDB(dst, b, h) do { _Pragma("unroll") for (int n = 0; n < 2; ++n) _Pragma("unroll") for (int k = 0; k < 2; ++k) dst[n][k] = *(const LAS bf16x8*)(lds + PG8_SB(b, h) + boff + n * 2048 + k * 1024); } while (0)
; #define PG8_MMA(ai, bj, At, Bt) do { __builtin_amdgcn_s_setprio(1); _Pragma("unroll") for (int m = 0; m < 4; ++m) _Pragma("unroll") for (int n = 0; n < 2; ++n) _Pragma("unroll") for (int k = 0; k < 2; ++k) \
;         acc[ai][bj][m][n] = __builtin_amdgcn_mfma_f32_16x16x32_bf16(Bt[n][k], At[m][k], acc[ai][bj][m][n], 0, 0, 0); __builtin_amdgcn_s_setprio(0); } while (0)
; #define PG8_WAIT_V(n) asm volatile("s_waitcnt vmcnt(" #n ")" ::: "memory")
; #define PG8_WAIT_L(n) asm volatile("s_waitcnt lgkmcnt(" #n ")" ::: "memory")
; #define PG8_BAR __builtin_amdgcn_s_barrier()
; #define PG8_SCHED __builtin_amdgcn_sched_barrier(0)
; template <class Epi, class Sched>
; __device__ __forceinline__ void gemm_phase(LAS unsigned char* lds, const int lda, const int ldb, const int K, const Sched& S, const Epi& E) {
;     ...
;             PG8_LDB(B0, 1, 0); PG8_LDB(B1, 1, 1); PG8_SCHED; PG8_LDA(At, 1, 0); PG8_STAGE(PG8_SA(0, 1), a2 + hstepA, voffA);
;             PG8_WAIT_V(8); PG8_WAIT_L(0); PG8_BAR; PG8_MMA(0, 0, At, B0); PG8_MMA(0, 1, At, B1); PG8_BAR; PG8_SCHED;
;             PG8_LDA(At, 1, 1); PG8_STAGE(PG8_SB(1, 0), b3, voffB); PG8_STAGE(PG8_SB(1, 1), b3 + hstepB, voffB); PG8_STAGE(PG8_SA(1, 0), a3, voffA);
;             PG8_WAIT_V(8); PG8_WAIT_L(0); PG8_BAR;
;             if (last) E.pre(cur, wr, fr, rsv);
;             PG8_MMA(1, 0, At, B0); PG8_MMA(1, 1, At, B1); PG8_BAR; PG8_SCHED;
;         }
;         if (wr == 0) PG8_BAR;
.Lpeel2_join:
	s_add_i32 s51, 0, 0x18000
	s_add_i32 s62, 0, 0x1c000
	v_add_u32_e32 v142, s51, v186
	v_add_u32_e32 v174, s62, v186
	ds_read_b128 v[130:133], v142
	ds_read_b128 v[134:137], v142 offset:1024
	ds_read_b128 v[138:141], v142 offset:2048
	ds_read_b128 v[142:145], v142 offset:3072
	ds_read_b128 v[146:149], v174
	ds_read_b128 v[150:153], v174 offset:1024
	ds_read_b128 v[170:173], v174 offset:2048
	ds_read_b128 v[174:177], v174 offset:3072
	s_add_u32 s22, s22, 0xb0000
	s_addc_u32 s23, s23, 0
	s_mov_b32 m0, s28
	ds_read_b128 v[178:181], v190 offset:32768
	ds_read_b128 v[182:185], v190 offset:33792
	ds_read_b128 v[196:199], v190 offset:34816
	ds_read_b128 v[200:203], v190 offset:35840
	ds_read_b128 v[204:207], v190 offset:36864
	ds_read_b128 v[208:211], v190 offset:37888
	ds_read_b128 v[212:215], v190 offset:38912
	ds_read_b128 v[216:219], v190 offset:39936
	global_load_lds_dwordx4 v154, s[22:23]
	s_mov_b32 m0, s29
	s_nop 0
	global_load_lds_dwordx4 v158, s[22:23]
	s_waitcnt vmcnt(8)
	s_waitcnt lgkmcnt(0)
	s_barrier
	v_mfma_f32_16x16x32_bf16 v[126:129], v[130:133], v[178:181], v[126:129]
	v_mfma_f32_16x16x32_bf16 v[122:125], v[138:141], v[178:181], v[122:125]
	v_mfma_f32_16x16x32_bf16 v[110:113], v[130:133], v[196:199], v[110:113]
	v_mfma_f32_16x16x32_bf16 v[106:109], v[138:141], v[196:199], v[106:109]
	v_mfma_f32_16x16x32_bf16 v[94:97], v[130:133], v[204:207], v[94:97]
	v_mfma_f32_16x16x32_bf16 v[90:93], v[138:141], v[204:207], v[90:93]
	v_mfma_f32_16x16x32_bf16 v[78:81], v[130:133], v[212:215], v[78:81]
	v_mfma_f32_16x16x32_bf16 v[74:77], v[138:141], v[212:215], v[74:77]
	v_mfma_f32_16x16x32_bf16 v[126:129], v[134:137], v[182:185], v[126:129]
	v_mfma_f32_16x16x32_bf16 v[122:125], v[142:145], v[182:185], v[122:125]
	v_mfma_f32_16x16x32_bf16 v[110:113], v[134:137], v[200:203], v[110:113]
	v_mfma_f32_16x16x32_bf16 v[106:109], v[142:145], v[200:203], v[106:109]
	v_mfma_f32_16x16x32_bf16 v[94:97], v[134:137], v[208:211], v[94:97]
	v_mfma_f32_16x16x32_bf16 v[90:93], v[142:145], v[208:211], v[90:93]
	v_mfma_f32_16x16x32_bf16 v[78:81], v[134:137], v[216:219], v[78:81]
	v_mfma_f32_16x16x32_bf16 v[74:77], v[142:145], v[216:219], v[74:77]
	v_mfma_f32_16x16x32_bf16 v[118:121], v[146:149], v[178:181], v[118:121]
	v_mfma_f32_16x16x32_bf16 v[114:117], v[170:173], v[178:181], v[114:117]
	v_mfma_f32_16x16x32_bf16 v[102:105], v[146:149], v[196:199], v[102:105]
	v_mfma_f32_16x16x32_bf16 v[98:101], v[170:173], v[196:199], v[98:101]
	v_mfma_f32_16x16x32_bf16 v[86:89], v[146:149], v[204:207], v[86:89]
	v_mfma_f32_16x16x32_bf16 v[82:85], v[170:173], v[204:207], v[82:85]
	v_mfma_f32_16x16x32_bf16 v[70:73], v[146:149], v[212:215], v[70:73]
	v_mfma_f32_16x16x32_bf16 v[66:69], v[170:173], v[212:215], v[66:69]
	v_mfma_f32_16x16x32_bf16 v[118:121], v[150:153], v[182:185], v[118:121]
	v_mfma_f32_16x16x32_bf16 v[114:117], v[174:177], v[182:185], v[114:117]
	v_mfma_f32_16x16x32_bf16 v[102:105], v[150:153], v[200:203], v[102:105]
	v_mfma_f32_16x16x32_bf16 v[98:101], v[174:177], v[200:203], v[98:101]
	v_mfma_f32_16x16x32_bf16 v[86:89], v[150:153], v[208:211], v[86:89]
	v_mfma_f32_16x16x32_bf16 v[82:85], v[174:177], v[208:211], v[82:85]
	v_mfma_f32_16x16x32_bf16 v[70:73], v[150:153], v[216:219], v[70:73]
	v_mfma_f32_16x16x32_bf16 v[66:69], v[174:177], v[216:219], v[66:69]
	s_barrier
	s_add_i32 s22, s51, s25
	s_mov_b32 m0, s22
	ds_read_b128 v[178:181], v190 offset:49152
	ds_read_b128 v[182:185], v190 offset:50176
	ds_read_b128 v[196:199], v190 offset:51200
	ds_read_b128 v[200:203], v190 offset:52224
	ds_read_b128 v[204:207], v190 offset:53248
	ds_read_b128 v[208:211], v190 offset:54272
	ds_read_b128 v[212:215], v190 offset:55296
	ds_read_b128 v[216:219], v190 offset:56320
	global_load_lds_dwordx4 v192, s[20:21]
	s_add_i32 m0, s22, 0x2000
	s_add_u32 s20, s20, 0xb0080
	s_addc_u32 s21, s21, 0
	s_add_i32 s22, s62, s25
	global_load_lds_dwordx4 v193, s[98:99]
	s_mov_b32 m0, s22
	s_nop 0
	global_load_lds_dwordx4 v156, s[20:21]
	s_add_i32 m0, s22, 0x2000
	s_nop 0
	global_load_lds_dwordx4 v160, s[20:21]
	s_mov_b32 m0, s33
	s_nop 0
	global_load_lds_dwordx4 v220, s[100:101]
	s_mov_b32 m0, s36
	s_nop 0
	global_load_lds_dwordx4 v221, s[100:101]
	s_waitcnt vmcnt(8)
	s_waitcnt lgkmcnt(0)
	s_barrier
	v_mfma_f32_16x16x32_bf16 v[62:65], v[130:133], v[178:181], v[62:65]
	v_mfma_f32_16x16x32_bf16 v[58:61], v[138:141], v[178:181], v[58:61]
	v_mfma_f32_16x16x32_bf16 v[46:49], v[130:133], v[196:199], v[46:49]
	v_mfma_f32_16x16x32_bf16 v[42:45], v[138:141], v[196:199], v[42:45]
	v_mfma_f32_16x16x32_bf16 v[30:33], v[130:133], v[204:207], v[30:33]
	v_mfma_f32_16x16x32_bf16 v[26:29], v[138:141], v[204:207], v[26:29]
	v_mfma_f32_16x16x32_bf16 v[14:17], v[130:133], v[212:215], v[14:17]
	v_mfma_f32_16x16x32_bf16 v[10:13], v[138:141], v[212:215], v[10:13]
	v_mfma_f32_16x16x32_bf16 v[62:65], v[134:137], v[182:185], v[62:65]
	v_mfma_f32_16x16x32_bf16 v[58:61], v[142:145], v[182:185], v[58:61]
	v_mfma_f32_16x16x32_bf16 v[46:49], v[134:137], v[200:203], v[46:49]
	v_mfma_f32_16x16x32_bf16 v[42:45], v[142:145], v[200:203], v[42:45]
	v_mfma_f32_16x16x32_bf16 v[30:33], v[134:137], v[208:211], v[30:33]
	v_mfma_f32_16x16x32_bf16 v[26:29], v[142:145], v[208:211], v[26:29]
	v_mfma_f32_16x16x32_bf16 v[14:17], v[134:137], v[216:219], v[14:17]
	v_mfma_f32_16x16x32_bf16 v[10:13], v[142:145], v[216:219], v[10:13]
	v_mfma_f32_16x16x32_bf16 v[54:57], v[146:149], v[178:181], v[54:57]
	v_mfma_f32_16x16x32_bf16 v[50:53], v[170:173], v[178:181], v[50:53]
	v_mfma_f32_16x16x32_bf16 v[38:41], v[146:149], v[196:199], v[38:41]
	v_mfma_f32_16x16x32_bf16 v[34:37], v[170:173], v[196:199], v[34:37]
	v_mfma_f32_16x16x32_bf16 v[22:25], v[146:149], v[204:207], v[22:25]
	v_mfma_f32_16x16x32_bf16 v[18:21], v[170:173], v[204:207], v[18:21]
	v_mfma_f32_16x16x32_bf16 v[6:9], v[146:149], v[212:215], v[6:9]
	v_mfma_f32_16x16x32_bf16 v[2:5], v[170:173], v[212:215], v[2:5]
	v_mfma_f32_16x16x32_bf16 v[54:57], v[150:153], v[182:185], v[54:57]
	v_mfma_f32_16x16x32_bf16 v[50:53], v[174:177], v[182:185], v[50:53]
	v_mfma_f32_16x16x32_bf16 v[38:41], v[150:153], v[200:203], v[38:41]
	v_mfma_f32_16x16x32_bf16 v[34:37], v[174:177], v[200:203], v[34:37]
	v_mfma_f32_16x16x32_bf16 v[22:25], v[150:153], v[208:211], v[22:25]
	v_mfma_f32_16x16x32_bf16 v[18:21], v[174:177], v[208:211], v[18:21]
	v_mfma_f32_16x16x32_bf16 v[6:9], v[150:153], v[216:219], v[6:9]
	v_mfma_f32_16x16x32_bf16 v[2:5], v[174:177], v[216:219], v[2:5]
	s_barrier
	s_add_i32 s50, s50, 2
	s_add_u32 s18, s18, 0x100
	s_addc_u32 s19, s19, 0
	s_add_u32 s48, s48, 0x100
	s_addc_u32 s49, s49, 0
	s_cmp_gt_u32 s50, 41
	s_cbranch_scc0 .LBB0_326
	s_and_b64 vcc, exec, s[12:13]
	s_cbranch_vccz .LBB0_329
	s_setprio 1
	s_barrier

; #define PG8_BAR __builtin_amdgcn_s_barrier()
; template <class Epi, class Sched>
; __device__ __forceinline__ void gemm_phase(LAS unsigned char* lds, const int lda, const int ldb, const int K, const Sched& S, const Epi& E) {
;     ...
;         if (wr == 0) PG8_BAR;
.LBB0_428:
	s_and_b64 vcc, exec, s[26:27]
	s_cbranch_vccz .LBB0_430
	s_setprio 1
	s_barrier

; #define PG8_STAGE(bufoff, gbase, voff) do { _Pragma("unroll") for (int _i = 0; _i < 2; ++_i) \
;         __builtin_amdgcn_global_load_lds((const unsigned*)((const char*)(gbase) + (voff)[_i]), (LAS unsigned*)(lds + (bufoff) + ldsw + _i * 8192), 16, 0, 0); } while (0)
; #define PG8_LDA(dst, b, h) do { _Pragma("unroll") for (int m = 0; m < 4; ++m) _Pragma("unroll") for (int k = 0; k < 2; ++k) dst[m][k] = *(const LAS bf16x8*)(lds + PG8_SA(b, h) + aoff + m * 2048 + k * 1024); } while (0)
; #define PG8_LDB(dst, b, h) do { _Pragma("unroll") for (int n = 0; n < 2; ++n) _Pragma("unroll") for (int k = 0; k < 2; ++k) dst[n][k] = *(const LAS bf16x8*)(lds + PG8_SB(b, h) + boff + n * 2048 + k * 1024); } while (0)
; #define PG8_MMA(ai, bj, At, Bt) do { __builtin_amdgcn_s_setprio(1); _Pragma("unroll") for (int m = 0; m < 4; ++m) _Pragma("unroll") for (int n = 0; n < 2; ++n) _Pragma("unroll") for (int k = 0; k < 2; ++k) \
;         acc[ai][bj][m][n] = __builtin_amdgcn_mfma_f32_16x16x32_bf16(Bt[n][k], At[m][k], acc[ai][bj][m][n], 0, 0, 0); __builtin_amdgcn_s_setprio(0); } while (0)
; #define PG8_WAIT_V(n) asm volatile("s_waitcnt vmcnt(" #n ")" ::: "memory")
; #define PG8_WAIT_L(n) asm volatile("s_waitcnt lgkmcnt(" #n ")" ::: "memory")
; #define PG8_BAR __builtin_amdgcn_s_barrier()
; #define PG8_SCHED __builtin_amdgcn_sched_barrier(0)
; template <class Epi, class Sched>
; __device__ __forceinline__ void gemm_phase(LAS unsigned char* lds, const int lda, const int ldb, const int K, const Sched& S, const Epi& E) {
;     ...
;         for (int t = 0; t < nt; t += 2) {
;             const bool last = (t == nt - 2);
;             const char* a1 = cA + (size_t)(t + 1) * kstep;
;             const char* a2 = last ? nA : cA + (size_t)(t + 2) * kstep; const char* b2 = last ? nB : cB + (size_t)(t + 2) * kstep;
;             const char* a3 = a2 + kstep; const char* b3 = b2 + kstep;
;             PG8_LDB(B0, 0, 0); PG8_LDB(B1, 0, 1); PG8_SCHED; PG8_LDA(At, 0, 0); PG8_STAGE(PG8_SA(1, 1), a1 + hstepA, voffA);
;             PG8_WAIT_V(8); PG8_WAIT_L(0); PG8_BAR; PG8_MMA(0, 0, At, B0); PG8_MMA(0, 1, At, B1); PG8_BAR; PG8_SCHED;
;             PG8_LDA(At, 0, 1); PG8_STAGE(PG8_SB(0, 0), b2, voffB); PG8_STAGE(PG8_SB(0, 1), b2 + hstepB, voffB); PG8_STAGE(PG8_SA(0, 0), a2, voffA);
;             PG8_WAIT_V(8); PG8_WAIT_L(0); PG8_BAR; PG8_MMA(1, 0, At, B0); PG8_MMA(1, 1, At, B1); PG8_BAR; PG8_SCHED;
.LBB0_839:
	v_add_u32_e32 v3, s43, v195
	ds_read_b128 v[62:65], v3
	ds_read_b128 v[66:69], v3 offset:1024
	ds_read_b128 v[86:89], v3 offset:2048
	ds_read_b128 v[90:93], v3 offset:3072
	v_add_u32_e32 v3, s44, v195
	ds_read_b128 v[110:113], v3
	ds_read_b128 v[114:117], v3 offset:1024
	ds_read_b128 v[142:145], v3 offset:2048
	ds_read_b128 v[146:149], v3 offset:3072
	s_add_u32 s20, s4, 0xfff50080
	s_addc_u32 s21, s5, -1
	s_cmp_eq_u32 s64, 4
	s_cselect_b32 s23, s17, s21
	s_cselect_b32 s22, s16, s20
	s_cselect_b32 s21, s19, s63
	s_cselect_b32 s20, s18, s15
	s_add_i32 m0, s28, 0xc000
	ds_read_b128 v[166:169], v201
	ds_read_b128 v[186:189], v201 offset:1024
	ds_read_b128 v[190:193], v201 offset:2048
	ds_read_b128 v[196:199], v201 offset:3072
	ds_read_b128 v[202:205], v201 offset:4096
	ds_read_b128 v[206:209], v201 offset:5120
	ds_read_b128 v[210:213], v201 offset:6144
	ds_read_b128 v[214:217], v201 offset:7168
	global_load_lds_dwordx4 v178, s[4:5]
	s_add_i32 m0, s28, 0xe000
	s_nop 0
	global_load_lds_dwordx4 v180, s[4:5]
	s_waitcnt vmcnt(8)
	s_waitcnt lgkmcnt(0)
	s_barrier
	v_mfma_f32_16x16x32_bf16 v[74:77], v[62:65], v[166:169], v[74:77]
	v_mfma_f32_16x16x32_bf16 v[70:73], v[86:89], v[166:169], v[70:73]
	v_mfma_f32_16x16x32_bf16 v[106:109], v[62:65], v[190:193], v[106:109]
	v_mfma_f32_16x16x32_bf16 v[102:105], v[86:89], v[190:193], v[102:105]
	v_mfma_f32_16x16x32_bf16 v[138:141], v[62:65], v[202:205], v[138:141]
	v_mfma_f32_16x16x32_bf16 v[126:129], v[86:89], v[202:205], v[126:129]
	v_mfma_f32_16x16x32_bf16 v[122:125], v[62:65], v[210:213], v[122:125]
	v_mfma_f32_16x16x32_bf16 v[118:121], v[86:89], v[210:213], v[118:121]
	v_mfma_f32_16x16x32_bf16 v[74:77], v[66:69], v[186:189], v[74:77]
	v_mfma_f32_16x16x32_bf16 v[70:73], v[90:93], v[186:189], v[70:73]
	v_mfma_f32_16x16x32_bf16 v[106:109], v[66:69], v[196:199], v[106:109]
	v_mfma_f32_16x16x32_bf16 v[102:105], v[90:93], v[196:199], v[102:105]
	v_mfma_f32_16x16x32_bf16 v[138:141], v[66:69], v[206:209], v[138:141]
	v_mfma_f32_16x16x32_bf16 v[126:129], v[90:93], v[206:209], v[126:129]
	v_mfma_f32_16x16x32_bf16 v[122:125], v[66:69], v[214:217], v[122:125]
	v_mfma_f32_16x16x32_bf16 v[118:121], v[90:93], v[214:217], v[118:121]
	v_mfma_f32_16x16x32_bf16 v[162:165], v[110:113], v[166:169], v[162:165]
	v_mfma_f32_16x16x32_bf16 v[158:161], v[142:145], v[166:169], v[158:161]
	v_mfma_f32_16x16x32_bf16 v[154:157], v[110:113], v[190:193], v[154:157]
	v_mfma_f32_16x16x32_bf16 v[150:153], v[142:145], v[190:193], v[150:153]
	v_mfma_f32_16x16x32_bf16 v[134:137], v[110:113], v[202:205], v[134:137]
	v_mfma_f32_16x16x32_bf16 v[130:133], v[142:145], v[202:205], v[130:133]
	v_mfma_f32_16x16x32_bf16 v[98:101], v[110:113], v[210:213], v[98:101]
	v_mfma_f32_16x16x32_bf16 v[94:97], v[142:145], v[210:213], v[94:97]
	v_mfma_f32_16x16x32_bf16 v[162:165], v[114:117], v[186:189], v[162:165]
	v_mfma_f32_16x16x32_bf16 v[158:161], v[146:149], v[186:189], v[158:161]
	v_mfma_f32_16x16x32_bf16 v[154:157], v[114:117], v[196:199], v[154:157]
	v_mfma_f32_16x16x32_bf16 v[150:153], v[146:149], v[196:199], v[150:153]
	v_mfma_f32_16x16x32_bf16 v[134:137], v[114:117], v[206:209], v[134:137]
	v_mfma_f32_16x16x32_bf16 v[130:133], v[146:149], v[206:209], v[130:133]
	v_mfma_f32_16x16x32_bf16 v[98:101], v[114:117], v[214:217], v[98:101]
	v_mfma_f32_16x16x32_bf16 v[94:97], v[146:149], v[214:217], v[94:97]
	s_barrier
	s_add_i32 s65, s43, s27
	s_mov_b32 m0, s65
	ds_read_b128 v[166:169], v201 offset:16384
	ds_read_b128 v[186:189], v201 offset:17408
	ds_read_b128 v[190:193], v201 offset:18432
	ds_read_b128 v[196:199], v201 offset:19456
	ds_read_b128 v[202:205], v201 offset:20480
	ds_read_b128 v[206:209], v201 offset:21504
	ds_read_b128 v[210:213], v201 offset:22528
	ds_read_b128 v[214:217], v201 offset:23552
	global_load_lds_dwordx4 v172, s[20:21]
	s_add_i32 m0, s65, 0x2000
	s_add_u32 s68, s20, 0x20000
	s_mov_b64 s[98:99], s[20:21]
	s_addc_u32 s69, s21, 0
	s_add_i32 s65, s44, s27
	global_load_lds_dwordx4 v176, s[20:21]
	s_mov_b32 m0, s65
	s_mov_b64 s[100:101], s[22:23]
	global_load_lds_dwordx4 v172, s[68:69]
	s_add_i32 m0, s65, 0x2000
	s_nop 0
	global_load_lds_dwordx4 v176, s[68:69]
	s_mov_b32 m0, s28
	s_nop 0
	global_load_lds_dwordx4 v170, s[22:23]
	s_mov_b32 m0, s29
	s_nop 0
	global_load_lds_dwordx4 v174, s[22:23]
	s_waitcnt vmcnt(8)
	s_waitcnt lgkmcnt(0)
	s_barrier
	v_mfma_f32_16x16x32_bf16 v[82:85], v[62:65], v[166:169], v[82:85]
	v_mfma_f32_16x16x32_bf16 v[78:81], v[86:89], v[166:169], v[78:81]
	v_mfma_f32_16x16x32_bf16 v[50:53], v[62:65], v[190:193], v[50:53]
	v_mfma_f32_16x16x32_bf16 v[46:49], v[86:89], v[190:193], v[46:49]
	v_mfma_f32_16x16x32_bf16 v[34:37], v[62:65], v[202:205], v[34:37]
	v_mfma_f32_16x16x32_bf16 v[30:33], v[86:89], v[202:205], v[30:33]
	v_mfma_f32_16x16x32_bf16 v[18:21], v[62:65], v[210:213], v[18:21]
	v_mfma_f32_16x16x32_bf16 v[14:17], v[86:89], v[210:213], v[14:17]
	v_mfma_f32_16x16x32_bf16 v[82:85], v[66:69], v[186:189], v[82:85]
	v_mfma_f32_16x16x32_bf16 v[78:81], v[90:93], v[186:189], v[78:81]
	v_mfma_f32_16x16x32_bf16 v[50:53], v[66:69], v[196:199], v[50:53]
	v_mfma_f32_16x16x32_bf16 v[46:49], v[90:93], v[196:199], v[46:49]
	v_mfma_f32_16x16x32_bf16 v[34:37], v[66:69], v[206:209], v[34:37]
	v_mfma_f32_16x16x32_bf16 v[30:33], v[90:93], v[206:209], v[30:33]
	v_mfma_f32_16x16x32_bf16 v[18:21], v[66:69], v[214:217], v[18:21]
	v_mfma_f32_16x16x32_bf16 v[14:17], v[90:93], v[214:217], v[14:17]
	v_mfma_f32_16x16x32_bf16 v[58:61], v[110:113], v[166:169], v[58:61]
	v_mfma_f32_16x16x32_bf16 v[54:57], v[142:145], v[166:169], v[54:57]
	v_mfma_f32_16x16x32_bf16 v[42:45], v[110:113], v[190:193], v[42:45]
	v_mfma_f32_16x16x32_bf16 v[38:41], v[142:145], v[190:193], v[38:41]
	v_mfma_f32_16x16x32_bf16 v[26:29], v[110:113], v[202:205], v[26:29]
	v_mfma_f32_16x16x32_bf16 v[22:25], v[142:145], v[202:205], v[22:25]
	v_mfma_f32_16x16x32_bf16 v[10:13], v[110:113], v[210:213], v[10:13]
	v_mfma_f32_16x16x32_bf16 v[4:7], v[142:145], v[210:213], v[6:9]
	v_mfma_f32_16x16x32_bf16 v[58:61], v[114:117], v[186:189], v[58:61]
	v_mfma_f32_16x16x32_bf16 v[54:57], v[146:149], v[186:189], v[54:57]
	v_mfma_f32_16x16x32_bf16 v[42:45], v[114:117], v[196:199], v[42:45]
	v_mfma_f32_16x16x32_bf16 v[38:41], v[146:149], v[196:199], v[38:41]
	v_mfma_f32_16x16x32_bf16 v[26:29], v[114:117], v[206:209], v[26:29]
	v_mfma_f32_16x16x32_bf16 v[22:25], v[146:149], v[206:209], v[22:25]
	v_mfma_f32_16x16x32_bf16 v[10:13], v[114:117], v[214:217], v[10:13]
	v_mfma_f32_16x16x32_bf16 v[4:7], v[146:149], v[214:217], v[4:7]
	s_barrier
; #define PG8_STAGE(bufoff, gbase, voff) do { _Pragma("unroll") for (int _i = 0; _i < 2; ++_i) \
;         __builtin_amdgcn_global_load_lds((const unsigned*)((const char*)(gbase) + (voff)[_i]), (LAS unsigned*)(lds + (bufoff) + ldsw + _i * 8192), 16, 0, 0); } while (0)
; #define PG8_LDA(dst, b, h) do { _Pragma("unroll") for (int m = 0; m < 4; ++m) _Pragma("unroll") for (int k = 0; k < 2; ++k) dst[m][k] = *(const LAS bf16x8*)(lds + PG8_SA(b, h) + aoff + m * 2048 + k * 1024); } while (0)
; #define PG8_LDB(dst, b, h) do { _Pragma("unroll") for (int n = 0; n < 2; ++n) _Pragma("unroll") for (int k = 0; k < 2; ++k) dst[n][k] = *(const LAS bf16x8*)(lds + PG8_SB(b, h) + boff + n * 2048 + k * 1024); } while (0)
; #define PG8_MMA(ai, bj, At, Bt) do { __builtin_amdgcn_s_setprio(1); _Pragma("unroll") for (int m = 0; m < 4; ++m) _Pragma("unroll") for (int n = 0; n < 2; ++n) _Pragma("unroll") for (int k = 0; k < 2; ++k) \
;         acc[ai][bj][m][n] = __builtin_amdgcn_mfma_f32_16x16x32_bf16(Bt[n][k], At[m][k], acc[ai][bj][m][n], 0, 0, 0); __builtin_amdgcn_s_setprio(0); } while (0)
; #define PG8_WAIT_V(n) asm volatile("s_waitcnt vmcnt(" #n ")" ::: "memory")
; #define PG8_WAIT_L(n) asm volatile("s_waitcnt lgkmcnt(" #n ")" ::: "memory")
; #define PG8_BAR __builtin_amdgcn_s_barrier()
; #define PG8_SCHED __builtin_amdgcn_sched_barrier(0)
; template <class Epi, class Sched>
; __device__ __forceinline__ void gemm_phase(LAS unsigned char* lds, const int lda, const int ldb, const int K, const Sched& S, const Epi& E) {
;     ...
;             PG8_LDB(B0, 1, 0); PG8_LDB(B1, 1, 1); PG8_SCHED; PG8_LDA(At, 1, 0); PG8_STAGE(PG8_SA(0, 1), a2 + hstepA, voffA);
;             PG8_WAIT_V(8); PG8_WAIT_L(0); PG8_BAR; PG8_MMA(0, 0, At, B0); PG8_MMA(0, 1, At, B1); PG8_BAR; PG8_SCHED;
;             PG8_LDA(At, 1, 1); PG8_STAGE(PG8_SB(1, 0), b3, voffB); PG8_STAGE(PG8_SB(1, 1), b3 + hstepB, voffB); PG8_STAGE(PG8_SA(1, 0), a3, voffA);
;             PG8_WAIT_V(8); PG8_WAIT_L(0); PG8_BAR;
;             if (last) E.pre(cur, wr, fr, rsv);
;             PG8_MMA(1, 0, At, B0); PG8_MMA(1, 1, At, B1); PG8_BAR; PG8_SCHED;
;         }
;         if (wr == 0) PG8_BAR;
	s_add_i32 s65, 0, 0x18000
	v_add_u32_e32 v3, s65, v195
	s_add_i32 s68, 0, 0x1c000
	ds_read_b128 v[62:65], v3
	ds_read_b128 v[66:69], v3 offset:1024
	ds_read_b128 v[86:89], v3 offset:2048
	ds_read_b128 v[90:93], v3 offset:3072
	v_add_u32_e32 v3, s68, v195
	ds_read_b128 v[110:113], v3
	ds_read_b128 v[114:117], v3 offset:1024
	ds_read_b128 v[142:145], v3 offset:2048
	ds_read_b128 v[146:149], v3 offset:3072
	s_add_u32 s22, s22, 0xb0000
	s_addc_u32 s23, s23, 0
	s_mov_b32 m0, s30
	ds_read_b128 v[166:169], v201 offset:32768
	ds_read_b128 v[186:189], v201 offset:33792
	ds_read_b128 v[190:193], v201 offset:34816
	ds_read_b128 v[196:199], v201 offset:35840
	ds_read_b128 v[202:205], v201 offset:36864
	ds_read_b128 v[206:209], v201 offset:37888
	ds_read_b128 v[210:213], v201 offset:38912
	ds_read_b128 v[214:217], v201 offset:39936
	global_load_lds_dwordx4 v170, s[22:23]
	s_mov_b32 m0, s31
	s_nop 0
	global_load_lds_dwordx4 v174, s[22:23]
	s_waitcnt vmcnt(8)
	s_waitcnt lgkmcnt(0)
	s_barrier
	v_mfma_f32_16x16x32_bf16 v[74:77], v[62:65], v[166:169], v[74:77]
	v_mfma_f32_16x16x32_bf16 v[70:73], v[86:89], v[166:169], v[70:73]
	v_mfma_f32_16x16x32_bf16 v[106:109], v[62:65], v[190:193], v[106:109]
	v_mfma_f32_16x16x32_bf16 v[102:105], v[86:89], v[190:193], v[102:105]
	v_mfma_f32_16x16x32_bf16 v[138:141], v[62:65], v[202:205], v[138:141]
	v_mfma_f32_16x16x32_bf16 v[126:129], v[86:89], v[202:205], v[126:129]
	v_mfma_f32_16x16x32_bf16 v[122:125], v[62:65], v[210:213], v[122:125]
	v_mfma_f32_16x16x32_bf16 v[118:121], v[86:89], v[210:213], v[118:121]
	v_mfma_f32_16x16x32_bf16 v[74:77], v[66:69], v[186:189], v[74:77]
	v_mfma_f32_16x16x32_bf16 v[70:73], v[90:93], v[186:189], v[70:73]
	v_mfma_f32_16x16x32_bf16 v[106:109], v[66:69], v[196:199], v[106:109]
	v_mfma_f32_16x16x32_bf16 v[102:105], v[90:93], v[196:199], v[102:105]
	v_mfma_f32_16x16x32_bf16 v[138:141], v[66:69], v[206:209], v[138:141]
	v_mfma_f32_16x16x32_bf16 v[126:129], v[90:93], v[206:209], v[126:129]
	v_mfma_f32_16x16x32_bf16 v[122:125], v[66:69], v[214:217], v[122:125]
	v_mfma_f32_16x16x32_bf16 v[118:121], v[90:93], v[214:217], v[118:121]
	v_mfma_f32_16x16x32_bf16 v[162:165], v[110:113], v[166:169], v[162:165]
	v_mfma_f32_16x16x32_bf16 v[158:161], v[142:145], v[166:169], v[158:161]
	v_mfma_f32_16x16x32_bf16 v[154:157], v[110:113], v[190:193], v[154:157]
	v_mfma_f32_16x16x32_bf16 v[150:153], v[142:145], v[190:193], v[150:153]
	v_mfma_f32_16x16x32_bf16 v[134:137], v[110:113], v[202:205], v[134:137]
	v_mfma_f32_16x16x32_bf16 v[130:133], v[142:145], v[202:205], v[130:133]
	v_mfma_f32_16x16x32_bf16 v[98:101], v[110:113], v[210:213], v[98:101]
	v_mfma_f32_16x16x32_bf16 v[94:97], v[142:145], v[210:213], v[94:97]
	v_mfma_f32_16x16x32_bf16 v[162:165], v[114:117], v[186:189], v[162:165]
	v_mfma_f32_16x16x32_bf16 v[158:161], v[146:149], v[186:189], v[158:161]
	v_mfma_f32_16x16x32_bf16 v[154:157], v[114:117], v[196:199], v[154:157]
	v_mfma_f32_16x16x32_bf16 v[150:153], v[146:149], v[196:199], v[150:153]
	v_mfma_f32_16x16x32_bf16 v[134:137], v[114:117], v[206:209], v[134:137]
	v_mfma_f32_16x16x32_bf16 v[130:133], v[146:149], v[206:209], v[130:133]
	v_mfma_f32_16x16x32_bf16 v[98:101], v[114:117], v[214:217], v[98:101]
	v_mfma_f32_16x16x32_bf16 v[94:97], v[146:149], v[214:217], v[94:97]
	s_barrier
	s_add_i32 s22, s65, s27
	s_mov_b32 m0, s22
	ds_read_b128 v[166:169], v201 offset:49152
	ds_read_b128 v[186:189], v201 offset:50176
	ds_read_b128 v[190:193], v201 offset:51200
	ds_read_b128 v[196:199], v201 offset:52224
	ds_read_b128 v[202:205], v201 offset:53248
	ds_read_b128 v[206:209], v201 offset:54272
	ds_read_b128 v[210:213], v201 offset:55296
	ds_read_b128 v[214:217], v201 offset:56320
	global_load_lds_dwordx4 v218, s[20:21]
	s_add_i32 m0, s22, 0x2000
	s_add_u32 s20, s20, 0x20080
	s_addc_u32 s21, s21, 0
	s_add_i32 s22, s68, s27
	global_load_lds_dwordx4 v219, s[98:99]
	s_mov_b32 m0, s22
	s_nop 0
	global_load_lds_dwordx4 v172, s[20:21]
	s_add_i32 m0, s22, 0x2000
	s_nop 0
	global_load_lds_dwordx4 v176, s[20:21]
	s_mov_b32 m0, s40
	s_nop 0
	global_load_lds_dwordx4 v220, s[100:101]
	s_mov_b32 m0, s41
	s_nop 0
	global_load_lds_dwordx4 v221, s[100:101]
	s_waitcnt vmcnt(8)
	s_waitcnt lgkmcnt(0)
	s_barrier
	v_mfma_f32_16x16x32_bf16 v[82:85], v[62:65], v[166:169], v[82:85]
	v_mfma_f32_16x16x32_bf16 v[78:81], v[86:89], v[166:169], v[78:81]
	v_mfma_f32_16x16x32_bf16 v[50:53], v[62:65], v[190:193], v[50:53]
	v_mfma_f32_16x16x32_bf16 v[46:49], v[86:89], v[190:193], v[46:49]
	v_mfma_f32_16x16x32_bf16 v[34:37], v[62:65], v[202:205], v[34:37]
	v_mfma_f32_16x16x32_bf16 v[30:33], v[86:89], v[202:205], v[30:33]
	v_mfma_f32_16x16x32_bf16 v[18:21], v[62:65], v[210:213], v[18:21]
	v_mfma_f32_16x16x32_bf16 v[14:17], v[86:89], v[210:213], v[14:17]
	v_mfma_f32_16x16x32_bf16 v[82:85], v[66:69], v[186:189], v[82:85]
	v_mfma_f32_16x16x32_bf16 v[78:81], v[90:93], v[186:189], v[78:81]
	v_mfma_f32_16x16x32_bf16 v[50:53], v[66:69], v[196:199], v[50:53]
	v_mfma_f32_16x16x32_bf16 v[46:49], v[90:93], v[196:199], v[46:49]
	v_mfma_f32_16x16x32_bf16 v[34:37], v[66:69], v[206:209], v[34:37]
	v_mfma_f32_16x16x32_bf16 v[30:33], v[90:93], v[206:209], v[30:33]
	v_mfma_f32_16x16x32_bf16 v[18:21], v[66:69], v[214:217], v[18:21]
	v_mfma_f32_16x16x32_bf16 v[14:17], v[90:93], v[214:217], v[14:17]
	v_mfma_f32_16x16x32_bf16 v[58:61], v[110:113], v[166:169], v[58:61]
	v_mfma_f32_16x16x32_bf16 v[54:57], v[142:145], v[166:169], v[54:57]
	v_mfma_f32_16x16x32_bf16 v[42:45], v[110:113], v[190:193], v[42:45]
	v_mfma_f32_16x16x32_bf16 v[38:41], v[142:145], v[190:193], v[38:41]
	v_mfma_f32_16x16x32_bf16 v[26:29], v[110:113], v[202:205], v[26:29]
	v_mfma_f32_16x16x32_bf16 v[22:25], v[142:145], v[202:205], v[22:25]
	v_mfma_f32_16x16x32_bf16 v[8:11], v[110:113], v[210:213], v[10:13]
	v_mfma_f32_16x16x32_bf16 v[4:7], v[142:145], v[210:213], v[4:7]
	v_mfma_f32_16x16x32_bf16 v[58:61], v[114:117], v[186:189], v[58:61]
	v_mfma_f32_16x16x32_bf16 v[54:57], v[146:149], v[186:189], v[54:57]
	v_mfma_f32_16x16x32_bf16 v[42:45], v[114:117], v[196:199], v[42:45]
	v_mfma_f32_16x16x32_bf16 v[38:41], v[146:149], v[196:199], v[38:41]
	v_mfma_f32_16x16x32_bf16 v[26:29], v[114:117], v[206:209], v[26:29]
	v_mfma_f32_16x16x32_bf16 v[22:25], v[146:149], v[206:209], v[22:25]
	v_mfma_f32_16x16x32_bf16 v[10:13], v[114:117], v[214:217], v[8:11]
	v_mfma_f32_16x16x32_bf16 v[6:9], v[146:149], v[214:217], v[4:7]
	s_barrier
	s_add_i32 s64, s64, 2
	s_add_u32 s4, s4, 0x100
	s_addc_u32 s5, s5, 0
	s_add_u32 s15, s15, 0x100
	s_addc_u32 s63, s63, 0
	s_cmp_gt_u32 s64, 5
	s_cbranch_scc0 .LBB0_839
	s_and_b64 vcc, exec, s[12:13]
	s_cbranch_vccz .LBB0_842
	s_setprio 1
	s_barrier

; #define PG8_STAGE(bufoff, gbase, voff) do { _Pragma("unroll") for (int _i = 0; _i < 2; ++_i) \
;         __builtin_amdgcn_global_load_lds((const unsigned*)((const char*)(gbase) + (voff)[_i]), (LAS unsigned*)(lds + (bufoff) + ldsw + _i * 8192), 16, 0, 0); } while (0)
; #define PG8_LDA(dst, b, h) do { _Pragma("unroll") for (int m = 0; m < 4; ++m) _Pragma("unroll") for (int k = 0; k < 2; ++k) dst[m][k] = *(const LAS bf16x8*)(lds + PG8_SA(b, h) + aoff + m * 2048 + k * 1024); } while (0)
; #define PG8_LDB(dst, b, h) do { _Pragma("unroll") for (int n = 0; n < 2; ++n) _Pragma("unroll") for (int k = 0; k < 2; ++k) dst[n][k] = *(const LAS bf16x8*)(lds + PG8_SB(b, h) + boff + n * 2048 + k * 1024); } while (0)
; #define PG8_MMA(ai, bj, At, Bt) do { __builtin_amdgcn_s_setprio(1); _Pragma("unroll") for (int m = 0; m < 4; ++m) _Pragma("unroll") for (int n = 0; n < 2; ++n) _Pragma("unroll") for (int k = 0; k < 2; ++k) \
;         acc[ai][bj][m][n] = __builtin_amdgcn_mfma_f32_16x16x32_bf16(Bt[n][k], At[m][k], acc[ai][bj][m][n], 0, 0, 0); __builtin_amdgcn_s_setprio(0); } while (0)
; #define PG8_WAIT_V(n) asm volatile("s_waitcnt vmcnt(" #n ")" ::: "memory")
; #define PG8_WAIT_L(n) asm volatile("s_waitcnt lgkmcnt(" #n ")" ::: "memory")
; #define PG8_BAR __builtin_amdgcn_s_barrier()
; #define PG8_SCHED __builtin_amdgcn_sched_barrier(0)
; template <class Epi, class Sched>
; __device__ __forceinline__ void gemm_phase(LAS unsigned char* lds, const int lda, const int ldb, const int K, const Sched& S, const Epi& E) {
;     ...
;             PG8_LDB(B0, 1, 0); PG8_LDB(B1, 1, 1); PG8_SCHED; PG8_LDA(At, 1, 0); PG8_STAGE(PG8_SA(0, 1), a2 + hstepA, voffA);
;             PG8_WAIT_V(8); PG8_WAIT_L(0); PG8_BAR; PG8_MMA(0, 0, At, B0); PG8_MMA(0, 1, At, B1); PG8_BAR; PG8_SCHED;
;             PG8_LDA(At, 1, 1); PG8_STAGE(PG8_SB(1, 0), b3, voffB); PG8_STAGE(PG8_SB(1, 1), b3 + hstepB, voffB); PG8_STAGE(PG8_SA(1, 0), a3, voffA);
;             PG8_WAIT_V(8); PG8_WAIT_L(0); PG8_BAR;
;             if (last) E.pre(cur, wr, fr, rsv);
;             PG8_MMA(1, 0, At, B0); PG8_MMA(1, 1, At, B1); PG8_BAR; PG8_SCHED;
;         }
;         if (wr == 0) PG8_BAR;
.Lpeel5_join:
	s_add_i32 s51, 0, 0x18000
	s_add_i32 s62, 0, 0x1c000
	v_add_u32_e32 v142, s51, v186
	v_add_u32_e32 v174, s62, v186
	ds_read_b128 v[130:133], v142
	ds_read_b128 v[134:137], v142 offset:1024
	ds_read_b128 v[138:141], v142 offset:2048
	ds_read_b128 v[142:145], v142 offset:3072
	ds_read_b128 v[146:149], v174
	ds_read_b128 v[150:153], v174 offset:1024
	ds_read_b128 v[170:173], v174 offset:2048
	ds_read_b128 v[174:177], v174 offset:3072
	s_add_u32 s28, s28, 0x40000
	s_addc_u32 s29, s29, 0
	s_mov_b32 m0, s35
	ds_read_b128 v[178:181], v190 offset:32768
	ds_read_b128 v[182:185], v190 offset:33792
	ds_read_b128 v[196:199], v190 offset:34816
	ds_read_b128 v[200:203], v190 offset:35840
	ds_read_b128 v[204:207], v190 offset:36864
	ds_read_b128 v[208:211], v190 offset:37888
	ds_read_b128 v[212:215], v190 offset:38912
	ds_read_b128 v[216:219], v190 offset:39936
	global_load_lds_dwordx4 v154, s[28:29]
	s_mov_b32 m0, s38
	s_nop 0
	global_load_lds_dwordx4 v158, s[28:29]
	s_waitcnt vmcnt(8)
	s_waitcnt lgkmcnt(0)
	s_barrier
	v_mfma_f32_16x16x32_bf16 v[126:129], v[130:133], v[178:181], v[126:129]
	v_mfma_f32_16x16x32_bf16 v[122:125], v[138:141], v[178:181], v[122:125]
	v_mfma_f32_16x16x32_bf16 v[110:113], v[130:133], v[196:199], v[110:113]
	v_mfma_f32_16x16x32_bf16 v[106:109], v[138:141], v[196:199], v[106:109]
	v_mfma_f32_16x16x32_bf16 v[94:97], v[130:133], v[204:207], v[94:97]
	v_mfma_f32_16x16x32_bf16 v[90:93], v[138:141], v[204:207], v[90:93]
	v_mfma_f32_16x16x32_bf16 v[78:81], v[130:133], v[212:215], v[78:81]
	v_mfma_f32_16x16x32_bf16 v[74:77], v[138:141], v[212:215], v[74:77]
	v_mfma_f32_16x16x32_bf16 v[126:129], v[134:137], v[182:185], v[126:129]
	v_mfma_f32_16x16x32_bf16 v[122:125], v[142:145], v[182:185], v[122:125]
	v_mfma_f32_16x16x32_bf16 v[110:113], v[134:137], v[200:203], v[110:113]
	v_mfma_f32_16x16x32_bf16 v[106:109], v[142:145], v[200:203], v[106:109]
	v_mfma_f32_16x16x32_bf16 v[94:97], v[134:137], v[208:211], v[94:97]
	v_mfma_f32_16x16x32_bf16 v[90:93], v[142:145], v[208:211], v[90:93]
	v_mfma_f32_16x16x32_bf16 v[78:81], v[134:137], v[216:219], v[78:81]
	v_mfma_f32_16x16x32_bf16 v[74:77], v[142:145], v[216:219], v[74:77]
	v_mfma_f32_16x16x32_bf16 v[118:121], v[146:149], v[178:181], v[118:121]
	v_mfma_f32_16x16x32_bf16 v[114:117], v[170:173], v[178:181], v[114:117]
	v_mfma_f32_16x16x32_bf16 v[102:105], v[146:149], v[196:199], v[102:105]
	v_mfma_f32_16x16x32_bf16 v[98:101], v[170:173], v[196:199], v[98:101]
	v_mfma_f32_16x16x32_bf16 v[86:89], v[146:149], v[204:207], v[86:89]
	v_mfma_f32_16x16x32_bf16 v[82:85], v[170:173], v[204:207], v[82:85]
	v_mfma_f32_16x16x32_bf16 v[70:73], v[146:149], v[212:215], v[70:73]
	v_mfma_f32_16x16x32_bf16 v[66:69], v[170:173], v[212:215], v[66:69]
	v_mfma_f32_16x16x32_bf16 v[118:121], v[150:153], v[182:185], v[118:121]
	v_mfma_f32_16x16x32_bf16 v[114:117], v[174:177], v[182:185], v[114:117]
	v_mfma_f32_16x16x32_bf16 v[102:105], v[150:153], v[200:203], v[102:105]
	v_mfma_f32_16x16x32_bf16 v[98:101], v[174:177], v[200:203], v[98:101]
	v_mfma_f32_16x16x32_bf16 v[86:89], v[150:153], v[208:211], v[86:89]
	v_mfma_f32_16x16x32_bf16 v[82:85], v[174:177], v[208:211], v[82:85]
	v_mfma_f32_16x16x32_bf16 v[70:73], v[150:153], v[216:219], v[70:73]
	v_mfma_f32_16x16x32_bf16 v[66:69], v[174:177], v[216:219], v[66:69]
	s_barrier
	s_add_i32 s28, s51, s31
	s_mov_b32 m0, s28
	ds_read_b128 v[178:181], v190 offset:49152
	ds_read_b128 v[182:185], v190 offset:50176
	ds_read_b128 v[196:199], v190 offset:51200
	ds_read_b128 v[200:203], v190 offset:52224
	ds_read_b128 v[204:207], v190 offset:53248
	ds_read_b128 v[208:211], v190 offset:54272
	ds_read_b128 v[212:215], v190 offset:55296
	ds_read_b128 v[216:219], v190 offset:56320
	global_load_lds_dwordx4 v192, s[26:27]
	s_add_i32 m0, s28, 0x2000
	s_add_u32 s26, s26, 0x40080
	s_addc_u32 s27, s27, 0
	s_add_i32 s28, s62, s31
	global_load_lds_dwordx4 v193, s[98:99]
	s_mov_b32 m0, s28
	s_nop 0
	global_load_lds_dwordx4 v156, s[26:27]
	s_add_i32 m0, s28, 0x2000
	s_nop 0
	global_load_lds_dwordx4 v160, s[26:27]
	s_mov_b32 m0, s41
	s_nop 0
	global_load_lds_dwordx4 v220, s[100:101]
	s_mov_b32 m0, s42
	s_nop 0
	global_load_lds_dwordx4 v221, s[100:101]
	s_waitcnt vmcnt(8)
	s_waitcnt lgkmcnt(0)
	s_barrier
	v_mfma_f32_16x16x32_bf16 v[62:65], v[130:133], v[178:181], v[62:65]
	v_mfma_f32_16x16x32_bf16 v[58:61], v[138:141], v[178:181], v[58:61]
	v_mfma_f32_16x16x32_bf16 v[46:49], v[130:133], v[196:199], v[46:49]
	v_mfma_f32_16x16x32_bf16 v[42:45], v[138:141], v[196:199], v[42:45]
	v_mfma_f32_16x16x32_bf16 v[30:33], v[130:133], v[204:207], v[30:33]
	v_mfma_f32_16x16x32_bf16 v[26:29], v[138:141], v[204:207], v[26:29]
	v_mfma_f32_16x16x32_bf16 v[14:17], v[130:133], v[212:215], v[14:17]
	v_mfma_f32_16x16x32_bf16 v[10:13], v[138:141], v[212:215], v[10:13]
	v_mfma_f32_16x16x32_bf16 v[62:65], v[134:137], v[182:185], v[62:65]
	v_mfma_f32_16x16x32_bf16 v[58:61], v[142:145], v[182:185], v[58:61]
	v_mfma_f32_16x16x32_bf16 v[46:49], v[134:137], v[200:203], v[46:49]
	v_mfma_f32_16x16x32_bf16 v[42:45], v[142:145], v[200:203], v[42:45]
	v_mfma_f32_16x16x32_bf16 v[30:33], v[134:137], v[208:211], v[30:33]
	v_mfma_f32_16x16x32_bf16 v[26:29], v[142:145], v[208:211], v[26:29]
	v_mfma_f32_16x16x32_bf16 v[14:17], v[134:137], v[216:219], v[14:17]
	v_mfma_f32_16x16x32_bf16 v[10:13], v[142:145], v[216:219], v[10:13]
	v_mfma_f32_16x16x32_bf16 v[54:57], v[146:149], v[178:181], v[54:57]
	v_mfma_f32_16x16x32_bf16 v[50:53], v[170:173], v[178:181], v[50:53]
	v_mfma_f32_16x16x32_bf16 v[38:41], v[146:149], v[196:199], v[38:41]
	v_mfma_f32_16x16x32_bf16 v[34:37], v[170:173], v[196:199], v[34:37]
	v_mfma_f32_16x16x32_bf16 v[22:25], v[146:149], v[204:207], v[22:25]
	v_mfma_f32_16x16x32_bf16 v[18:21], v[170:173], v[204:207], v[18:21]
	v_mfma_f32_16x16x32_bf16 v[6:9], v[146:149], v[212:215], v[6:9]
	v_mfma_f32_16x16x32_bf16 v[2:5], v[170:173], v[212:215], v[2:5]
	v_mfma_f32_16x16x32_bf16 v[54:57], v[150:153], v[182:185], v[54:57]
	v_mfma_f32_16x16x32_bf16 v[50:53], v[174:177], v[182:185], v[50:53]
	v_mfma_f32_16x16x32_bf16 v[38:41], v[150:153], v[200:203], v[38:41]
	v_mfma_f32_16x16x32_bf16 v[34:37], v[174:177], v[200:203], v[34:37]
	v_mfma_f32_16x16x32_bf16 v[22:25], v[150:153], v[208:211], v[22:25]
	v_mfma_f32_16x16x32_bf16 v[18:21], v[174:177], v[208:211], v[18:21]
	v_mfma_f32_16x16x32_bf16 v[6:9], v[150:153], v[216:219], v[6:9]
	v_mfma_f32_16x16x32_bf16 v[2:5], v[174:177], v[216:219], v[2:5]
	s_barrier
	s_add_i32 s23, s23, 2
	s_add_u32 s24, s24, 0x100
	s_addc_u32 s25, s25, 0
	s_add_u32 s15, s15, 0x100
	s_addc_u32 s17, s17, 0
	s_cmp_gt_u32 s23, 13
	s_cbranch_scc0 .LBB0_956
	s_and_b64 vcc, exec, s[12:13]
	s_cbranch_vccz .LBB0_959
	s_setprio 1
	s_barrier

; #define PG8_STAGE(bufoff, gbase, voff) do { _Pragma("unroll") for (int _i = 0; _i < 2; ++_i) \
;         __builtin_amdgcn_global_load_lds((const unsigned*)((const char*)(gbase) + (voff)[_i]), (LAS unsigned*)(lds + (bufoff) + ldsw + _i * 8192), 16, 0, 0); } while (0)
; #define PG8_LDA(dst, b, h) do { _Pragma("unroll") for (int m = 0; m < 4; ++m) _Pragma("unroll") for (int k = 0; k < 2; ++k) dst[m][k] = *(const LAS bf16x8*)(lds + PG8_SA(b, h) + aoff + m * 2048 + k * 1024); } while (0)
; #define PG8_LDB(dst, b, h) do { _Pragma("unroll") for (int n = 0; n < 2; ++n) _Pragma("unroll") for (int k = 0; k < 2; ++k) dst[n][k] = *(const LAS bf16x8*)(lds + PG8_SB(b, h) + boff + n * 2048 + k * 1024); } while (0)
; #define PG8_MMA(ai, bj, At, Bt) do { __builtin_amdgcn_s_setprio(1); _Pragma("unroll") for (int m = 0; m < 4; ++m) _Pragma("unroll") for (int n = 0; n < 2; ++n) _Pragma("unroll") for (int k = 0; k < 2; ++k) \
;         acc[ai][bj][m][n] = __builtin_amdgcn_mfma_f32_16x16x32_bf16(Bt[n][k], At[m][k], acc[ai][bj][m][n], 0, 0, 0); __builtin_amdgcn_s_setprio(0); } while (0)
; #define PG8_WAIT_V(n) asm volatile("s_waitcnt vmcnt(" #n ")" ::: "memory")
; #define PG8_WAIT_L(n) asm volatile("s_waitcnt lgkmcnt(" #n ")" ::: "memory")
; #define PG8_BAR __builtin_amdgcn_s_barrier()
; #define PG8_SCHED __builtin_amdgcn_sched_barrier(0)
; template <class Epi, class Sched>
; __device__ __forceinline__ void gemm_phase(LAS unsigned char* lds, const int lda, const int ldb, const int K, const Sched& S, const Epi& E) {
;     ...
;             PG8_LDB(B0, 1, 0); PG8_LDB(B1, 1, 1); PG8_SCHED; PG8_LDA(At, 1, 0); PG8_STAGE(PG8_SA(0, 1), a2 + hstepA, voffA);
;             PG8_WAIT_V(8); PG8_WAIT_L(0); PG8_BAR; PG8_MMA(0, 0, At, B0); PG8_MMA(0, 1, At, B1); PG8_BAR; PG8_SCHED;
;             PG8_LDA(At, 1, 1); PG8_STAGE(PG8_SB(1, 0), b3, voffB); PG8_STAGE(PG8_SB(1, 1), b3 + hstepB, voffB); PG8_STAGE(PG8_SA(1, 0), a3, voffA);
;             PG8_WAIT_V(8); PG8_WAIT_L(0); PG8_BAR;
;             if (last) E.pre(cur, wr, fr, rsv);
;             PG8_MMA(1, 0, At, B0); PG8_MMA(1, 1, At, B1); PG8_BAR; PG8_SCHED;
;         }
;         if (wr == 0) PG8_BAR;
.Lpeel7_join:
	s_add_i32 s42, 0, 0x18000
	s_add_i32 s43, 0, 0x1c000
	v_add_u32_e32 v162, s42, v149
	v_add_u32_e32 v178, s43, v149
	ds_read_b128 v[144:147], v162
	ds_read_b128 v[154:157], v162 offset:1024
	ds_read_b128 v[158:161], v162 offset:2048
	ds_read_b128 v[162:165], v162 offset:3072
	ds_read_b128 v[166:169], v178
	ds_read_b128 v[170:173], v178 offset:1024
	ds_read_b128 v[174:177], v178 offset:2048
	ds_read_b128 v[178:181], v178 offset:3072
	s_add_u32 s18, s18, 0xb0000
	s_addc_u32 s19, s19, 0
	s_mov_b32 m0, s26
	ds_read_b128 v[182:185], v153 offset:32768
	ds_read_b128 v[186:189], v153 offset:33792
	ds_read_b128 v[190:193], v153 offset:34816
	ds_read_b128 v[194:197], v153 offset:35840
	ds_read_b128 v[198:201], v153 offset:36864
	ds_read_b128 v[202:205], v153 offset:37888
	ds_read_b128 v[206:209], v153 offset:38912
	ds_read_b128 v[210:213], v153 offset:39936
	global_load_lds_dwordx4 v134, s[18:19]
	s_mov_b32 m0, s27
	s_nop 0
	global_load_lds_dwordx4 v130, s[18:19]
	s_waitcnt vmcnt(8)
	s_waitcnt lgkmcnt(0)
	s_barrier
	v_mfma_f32_16x16x32_bf16 v[124:127], v[144:147], v[182:185], v[124:127]
	v_mfma_f32_16x16x32_bf16 v[120:123], v[158:161], v[182:185], v[120:123]
	v_mfma_f32_16x16x32_bf16 v[112:115], v[144:147], v[190:193], v[112:115]
	v_mfma_f32_16x16x32_bf16 v[104:107], v[158:161], v[190:193], v[104:107]
	v_mfma_f32_16x16x32_bf16 v[96:99], v[144:147], v[198:201], v[96:99]
	v_mfma_f32_16x16x32_bf16 v[88:91], v[158:161], v[198:201], v[88:91]
	v_mfma_f32_16x16x32_bf16 v[80:83], v[144:147], v[206:209], v[80:83]
	v_mfma_f32_16x16x32_bf16 v[72:75], v[158:161], v[206:209], v[72:75]
	v_mfma_f32_16x16x32_bf16 v[124:127], v[154:157], v[186:189], v[124:127]
	v_mfma_f32_16x16x32_bf16 v[120:123], v[162:165], v[186:189], v[120:123]
	v_mfma_f32_16x16x32_bf16 v[112:115], v[154:157], v[194:197], v[112:115]
	v_mfma_f32_16x16x32_bf16 v[104:107], v[162:165], v[194:197], v[104:107]
	v_mfma_f32_16x16x32_bf16 v[96:99], v[154:157], v[202:205], v[96:99]
	v_mfma_f32_16x16x32_bf16 v[88:91], v[162:165], v[202:205], v[88:91]
	v_mfma_f32_16x16x32_bf16 v[80:83], v[154:157], v[210:213], v[80:83]
	v_mfma_f32_16x16x32_bf16 v[72:75], v[162:165], v[210:213], v[72:75]
	v_mfma_f32_16x16x32_bf16 v[116:119], v[166:169], v[182:185], v[116:119]
	v_mfma_f32_16x16x32_bf16 v[108:111], v[174:177], v[182:185], v[108:111]
	v_mfma_f32_16x16x32_bf16 v[100:103], v[166:169], v[190:193], v[100:103]
	v_mfma_f32_16x16x32_bf16 v[92:95], v[174:177], v[190:193], v[92:95]
	v_mfma_f32_16x16x32_bf16 v[84:87], v[166:169], v[198:201], v[84:87]
	v_mfma_f32_16x16x32_bf16 v[76:79], v[174:177], v[198:201], v[76:79]
	v_mfma_f32_16x16x32_bf16 v[68:71], v[166:169], v[206:209], v[68:71]
	v_mfma_f32_16x16x32_bf16 v[64:67], v[174:177], v[206:209], v[64:67]
	v_mfma_f32_16x16x32_bf16 v[116:119], v[170:173], v[186:189], v[116:119]
	v_mfma_f32_16x16x32_bf16 v[108:111], v[178:181], v[186:189], v[108:111]
	v_mfma_f32_16x16x32_bf16 v[100:103], v[170:173], v[194:197], v[100:103]
	v_mfma_f32_16x16x32_bf16 v[92:95], v[178:181], v[194:197], v[92:95]
	v_mfma_f32_16x16x32_bf16 v[84:87], v[170:173], v[202:205], v[84:87]
	v_mfma_f32_16x16x32_bf16 v[76:79], v[178:181], v[202:205], v[76:79]
	v_mfma_f32_16x16x32_bf16 v[68:71], v[170:173], v[210:213], v[68:71]
	v_mfma_f32_16x16x32_bf16 v[64:67], v[178:181], v[210:213], v[64:67]
	s_barrier
	s_add_i32 s18, s42, s21
	s_mov_b32 m0, s18
	ds_read_b128 v[182:185], v153 offset:49152
	ds_read_b128 v[186:189], v153 offset:50176
	ds_read_b128 v[190:193], v153 offset:51200
	ds_read_b128 v[194:197], v153 offset:52224
	ds_read_b128 v[198:201], v153 offset:53248
	ds_read_b128 v[202:205], v153 offset:54272
	ds_read_b128 v[206:209], v153 offset:55296
	ds_read_b128 v[210:213], v153 offset:56320
	global_load_lds_dwordx4 v214, s[16:17]
	s_add_i32 m0, s18, 0x2000
	s_add_u32 s16, s16, 0xb0080
	s_addc_u32 s17, s17, 0
	s_add_i32 s18, s43, s21
	global_load_lds_dwordx4 v215, s[98:99]
	s_mov_b32 m0, s18
	s_nop 0
	global_load_lds_dwordx4 v132, s[16:17]
	s_add_i32 m0, s18, 0x2000
	s_nop 0
	global_load_lds_dwordx4 v128, s[16:17]
	s_mov_b32 m0, s29
	s_nop 0
	global_load_lds_dwordx4 v216, s[100:101]
	s_mov_b32 m0, s30
	s_nop 0
	global_load_lds_dwordx4 v217, s[100:101]
	s_waitcnt vmcnt(8)
	s_waitcnt lgkmcnt(0)
	s_barrier
	v_mfma_f32_16x16x32_bf16 v[60:63], v[144:147], v[182:185], v[60:63]
	v_mfma_f32_16x16x32_bf16 v[56:59], v[158:161], v[182:185], v[56:59]
	v_mfma_f32_16x16x32_bf16 v[48:51], v[144:147], v[190:193], v[48:51]
	v_mfma_f32_16x16x32_bf16 v[40:43], v[158:161], v[190:193], v[40:43]
	v_mfma_f32_16x16x32_bf16 v[32:35], v[144:147], v[198:201], v[32:35]
	v_mfma_f32_16x16x32_bf16 v[24:27], v[158:161], v[198:201], v[24:27]
	v_mfma_f32_16x16x32_bf16 v[16:19], v[144:147], v[206:209], v[16:19]
	v_mfma_f32_16x16x32_bf16 v[8:11], v[158:161], v[206:209], v[8:11]
	v_mfma_f32_16x16x32_bf16 v[60:63], v[154:157], v[186:189], v[60:63]
	v_mfma_f32_16x16x32_bf16 v[56:59], v[162:165], v[186:189], v[56:59]
	v_mfma_f32_16x16x32_bf16 v[48:51], v[154:157], v[194:197], v[48:51]
	v_mfma_f32_16x16x32_bf16 v[40:43], v[162:165], v[194:197], v[40:43]
	v_mfma_f32_16x16x32_bf16 v[32:35], v[154:157], v[202:205], v[32:35]
	v_mfma_f32_16x16x32_bf16 v[24:27], v[162:165], v[202:205], v[24:27]
	v_mfma_f32_16x16x32_bf16 v[16:19], v[154:157], v[210:213], v[16:19]
	v_mfma_f32_16x16x32_bf16 v[8:11], v[162:165], v[210:213], v[8:11]
	v_mfma_f32_16x16x32_bf16 v[52:55], v[166:169], v[182:185], v[52:55]
	v_mfma_f32_16x16x32_bf16 v[44:47], v[174:177], v[182:185], v[44:47]
	v_mfma_f32_16x16x32_bf16 v[36:39], v[166:169], v[190:193], v[36:39]
	v_mfma_f32_16x16x32_bf16 v[28:31], v[174:177], v[190:193], v[28:31]
	v_mfma_f32_16x16x32_bf16 v[20:23], v[166:169], v[198:201], v[20:23]
	v_mfma_f32_16x16x32_bf16 v[12:15], v[174:177], v[198:201], v[12:15]
	v_mfma_f32_16x16x32_bf16 v[4:7], v[166:169], v[206:209], v[4:7]
	v_mfma_f32_16x16x32_bf16 v[0:3], v[174:177], v[206:209], v[0:3]
	v_mfma_f32_16x16x32_bf16 v[52:55], v[170:173], v[186:189], v[52:55]
	v_mfma_f32_16x16x32_bf16 v[44:47], v[178:181], v[186:189], v[44:47]
	v_mfma_f32_16x16x32_bf16 v[36:39], v[170:173], v[194:197], v[36:39]
	v_mfma_f32_16x16x32_bf16 v[28:31], v[178:181], v[194:197], v[28:31]
	v_mfma_f32_16x16x32_bf16 v[20:23], v[170:173], v[202:205], v[20:23]
	v_mfma_f32_16x16x32_bf16 v[12:15], v[178:181], v[202:205], v[12:15]
	v_mfma_f32_16x16x32_bf16 v[4:7], v[170:173], v[210:213], v[4:7]
	v_mfma_f32_16x16x32_bf16 v[0:3], v[178:181], v[210:213], v[0:3]
	s_barrier
	s_add_i32 s41, s41, 2
	s_add_u32 s14, s14, 0x100
	s_addc_u32 s15, s15, 0
	s_add_u32 s39, s39, 0x100
	s_addc_u32 s40, s40, 0
	s_cmp_gt_u32 s41, 41
	s_cbranch_scc0 .LBB0_1136
	s_and_b64 vcc, exec, s[8:9]
	s_cbranch_vccz .LBB0_1139
	s_setprio 1
	s_barrier
